# E12: v50 + inline-constant 0 as srcC of the two chain-opening QK MFMAs per tile (no zero-tile register read)
# speedup vs baseline: 1.0200x; 1.0200x over previous
.LBB0_731:
	s_mov_b32 s44, s29
	s_mov_b32 s28, s25
	v_add_u32_e32 v195, s45, v190
	ds_read_b64_tr_b16 v[196:197], v195 offset:24576
	ds_read_b64_tr_b16 v[198:199], v195 offset:25088
	v_add_f32_e32 v88, v68, v69
	v_add_f32_e32 v88, v70, v88
	v_add_f32_e32 v88, v71, v88
	v_add_f32_e32 v88, v72, v88
	v_add_f32_e32 v88, v73, v88
	v_cvt_pk_bf16_f32 v152, v68, v69
	v_cvt_pk_bf16_f32 v153, v70, v71
	v_mfma_f32_32x32x16_bf16 v[100:115], v[84:87], v[160:163], 0
	ds_read_b64_tr_b16 v[68:69], v195 offset:28672
	ds_read_b64_tr_b16 v[70:71], v195 offset:29184
	v_add_f32_e32 v84, v74, v88
	v_add_f32_e32 v84, v75, v84
	v_add_f32_e32 v84, v76, v84
	v_add_f32_e32 v132, v77, v84
	v_mfma_f32_32x32x16_bf16 v[84:99], v[168:171], v[160:163], 0
	v_cvt_pk_bf16_f32 v154, v72, v73
	v_cvt_pk_bf16_f32 v155, v74, v75
	ds_read_b64_tr_b16 v[72:73], v195 offset:25600
	ds_read_b64_tr_b16 v[74:75], v195 offset:26112
	v_add_f32_e32 v132, v78, v132
	v_add_f32_e32 v132, v79, v132
	v_add_f32_e32 v132, v80, v132
	v_add_f32_e32 v132, v81, v132
	v_cvt_pk_bf16_f32 v148, v76, v77
	v_cvt_pk_bf16_f32 v149, v78, v79
	v_mfma_f32_32x32x16_bf16 v[100:115], v[172:175], v[156:159], v[100:115]
	ds_read_b64_tr_b16 v[76:77], v195 offset:29696
	ds_read_b64_tr_b16 v[78:79], v195 offset:30208
	v_mfma_f32_32x32x16_bf16 v[84:99], v[164:167], v[156:159], v[84:99]
	v_add_f32_e32 v132, v82, v132
	v_add_f32_e32 v132, v83, v132
	v_add_f32_e32 v132, v52, v132
	v_add_f32_e32 v132, v53, v132
	v_cvt_pk_bf16_f32 v150, v80, v81
	v_cvt_pk_bf16_f32 v151, v82, v83
	ds_read_b64_tr_b16 v[80:81], v195 offset:26624
	ds_read_b64_tr_b16 v[82:83], v195 offset:27136
	v_mfma_f32_32x32x16_bf16 v[100:115], v[128:131], v[144:147], v[100:115]
	v_add_f32_e32 v128, v54, v132
	v_add_f32_e32 v128, v55, v128
	v_add_f32_e32 v128, v56, v128
	v_add_f32_e32 v128, v57, v128
	v_cvt_pk_bf16_f32 v140, v52, v53
	v_cvt_pk_bf16_f32 v141, v54, v55
	ds_read_b64_tr_b16 v[52:53], v195 offset:30720
	ds_read_b64_tr_b16 v[54:55], v195 offset:31232
	v_mfma_f32_32x32x16_bf16 v[84:99], v[124:127], v[144:147], v[84:99]
	v_add_f32_e32 v124, v58, v128
	v_add_f32_e32 v124, v59, v124
	v_add_f32_e32 v124, v60, v124
	v_add_f32_e32 v124, v61, v124
	v_cvt_pk_bf16_f32 v142, v56, v57
	v_cvt_pk_bf16_f32 v143, v58, v59
	ds_read_b64_tr_b16 v[56:57], v195 offset:27648
	ds_read_b64_tr_b16 v[58:59], v195 offset:28160
	v_mfma_f32_32x32x16_bf16 v[100:115], v[120:123], v[136:139], v[100:115]
	v_add_f32_e32 v120, v62, v124
	v_add_f32_e32 v120, v63, v120
	v_add_f32_e32 v120, v64, v120
	v_add_f32_e32 v120, v65, v120
	v_cvt_pk_bf16_f32 v132, v60, v61
	v_cvt_pk_bf16_f32 v133, v62, v63
	ds_read_b64_tr_b16 v[60:61], v195 offset:31744
	ds_read_b64_tr_b16 v[62:63], v195 offset:32256
	v_mfma_f32_32x32x16_bf16 v[84:99], v[116:119], v[136:139], v[84:99]
	v_add_f32_e32 v116, v66, v120
	v_add_f32_e32 v195, v67, v116
	v_cvt_pk_bf16_f32 v134, v64, v65
	v_cvt_pk_bf16_f32 v135, v66, v67
	s_add_i32 m0, s25, s59
	v_lshl_add_u64 v[64:65], v[0:1], 0, s[76:77]
	global_load_lds_dwordx4 v[64:65], off
	s_add_i32 m0, s44, s58
	v_lshl_add_u64 v[64:65], v[184:185], 0, s[34:35]
	global_load_lds_dwordx4 v[64:65], off
	s_waitcnt lgkmcnt(14)
	v_mfma_f32_32x32x16_bf16 v[4:19], v[152:155], v[196:199], v[4:19]
	v_exp_f32_e32 v100, v100
	v_exp_f32_e32 v101, v101
	v_exp_f32_e32 v102, v102
	v_exp_f32_e32 v103, v103
	s_waitcnt lgkmcnt(12)
	v_mfma_f32_32x32x16_bf16 v[20:35], v[152:155], v[68:71], v[20:35]
	v_exp_f32_e32 v104, v104
	v_exp_f32_e32 v105, v105
	v_exp_f32_e32 v106, v106
	v_exp_f32_e32 v107, v107
	v_add_u32_e32 v68, s44, v191
	ds_read_b128 v[64:67], v68
	ds_read_b128 v[120:123], v68 offset:512
	s_waitcnt lgkmcnt(12)
	v_mfma_f32_32x32x16_bf16 v[4:19], v[148:151], v[72:75], v[4:19]
	v_exp_f32_e32 v108, v108
	v_exp_f32_e32 v109, v109
	v_exp_f32_e32 v110, v110
	v_exp_f32_e32 v111, v111
	ds_read_b128 v[124:127], v68 offset:2048
	ds_read_b128 v[128:131], v68 offset:2560
	s_waitcnt lgkmcnt(12)
	v_mfma_f32_32x32x16_bf16 v[20:35], v[148:151], v[76:79], v[20:35]
	v_exp_f32_e32 v112, v112
	v_exp_f32_e32 v113, v113
	v_exp_f32_e32 v114, v114
	v_exp_f32_e32 v115, v115
	ds_read_b128 v[164:167], v68 offset:4096
	ds_read_b128 v[168:171], v68 offset:4608
	s_waitcnt lgkmcnt(12)
	v_mfma_f32_32x32x16_bf16 v[4:19], v[140:143], v[80:83], v[4:19]
	v_exp_f32_e32 v84, v84
	v_exp_f32_e32 v85, v85
	v_exp_f32_e32 v86, v86
	v_exp_f32_e32 v87, v87
	ds_read_b128 v[172:175], v68 offset:6144
	ds_read_b128 v[116:119], v68 offset:6656
	s_waitcnt lgkmcnt(12)
	v_mfma_f32_32x32x16_bf16 v[20:35], v[140:143], v[52:55], v[20:35]
	v_exp_f32_e32 v88, v88
	v_exp_f32_e32 v89, v89
	v_exp_f32_e32 v90, v90
	v_exp_f32_e32 v91, v91
	s_waitcnt lgkmcnt(10)
	v_mfma_f32_32x32x16_bf16 v[4:19], v[132:135], v[56:59], v[4:19]
	v_exp_f32_e32 v92, v92
	v_exp_f32_e32 v93, v93
	v_exp_f32_e32 v94, v94
	v_exp_f32_e32 v95, v95
	s_waitcnt lgkmcnt(8)
	v_mfma_f32_32x32x16_bf16 v[20:35], v[132:135], v[60:63], v[20:35]
	v_exp_f32_e32 v96, v96
	v_exp_f32_e32 v97, v97
	v_exp_f32_e32 v98, v98
	v_exp_f32_e32 v99, v99
	s_waitcnt vmcnt(2) lgkmcnt(0)
	s_barrier
	s_add_i32 s25, s44, 0x2000
	s_cmpk_lg_i32 s44, 0x4000
	s_cselect_b32 s25, s25, 0
	v_add_u32_e32 v200, s28, v190
	ds_read_b64_tr_b16 v[196:197], v200 offset:24576
	ds_read_b64_tr_b16 v[198:199], v200 offset:25088
	v_mfma_f32_32x32x16_bf16 v[68:83], v[64:67], v[160:163], 0
	v_add_f32_e32 v52, v100, v101
	v_add_f32_e32 v52, v102, v52
	v_add_f32_e32 v52, v103, v52
	v_add_f32_e32 v52, v104, v52
	v_add_f32_e32 v52, v105, v52
	v_cvt_pk_bf16_f32 v152, v100, v101
	v_cvt_pk_bf16_f32 v153, v102, v103
	ds_read_b64_tr_b16 v[100:101], v200 offset:28672
	ds_read_b64_tr_b16 v[102:103], v200 offset:29184
	v_add_f32_e32 v52, v106, v52
	v_add_f32_e32 v52, v107, v52
	v_add_f32_e32 v52, v108, v52
	v_add_f32_e32 v132, v109, v52
	v_mfma_f32_32x32x16_bf16 v[52:67], v[120:123], v[160:163], 0
	v_cvt_pk_bf16_f32 v154, v104, v105
	v_cvt_pk_bf16_f32 v155, v106, v107
	ds_read_b64_tr_b16 v[104:105], v200 offset:25600
	ds_read_b64_tr_b16 v[106:107], v200 offset:26112
	v_mfma_f32_32x32x16_bf16 v[68:83], v[124:127], v[156:159], v[68:83]
	v_add_f32_e32 v120, v110, v132
	v_add_f32_e32 v120, v111, v120
	v_add_f32_e32 v120, v112, v120
	v_add_f32_e32 v120, v113, v120
	v_cvt_pk_bf16_f32 v148, v108, v109
	v_cvt_pk_bf16_f32 v149, v110, v111
	ds_read_b64_tr_b16 v[108:109], v200 offset:29696
	ds_read_b64_tr_b16 v[110:111], v200 offset:30208
	v_mfma_f32_32x32x16_bf16 v[52:67], v[128:131], v[156:159], v[52:67]
	v_add_f32_e32 v120, v114, v120
	v_add_f32_e32 v120, v115, v120
	v_add_f32_e32 v120, v84, v120
	v_add_f32_e32 v120, v85, v120
	v_cvt_pk_bf16_f32 v150, v112, v113
	v_cvt_pk_bf16_f32 v151, v114, v115
	ds_read_b64_tr_b16 v[112:113], v200 offset:26624
	ds_read_b64_tr_b16 v[114:115], v200 offset:27136
	v_mfma_f32_32x32x16_bf16 v[68:83], v[164:167], v[144:147], v[68:83]
	v_add_f32_e32 v120, v86, v120
	v_add_f32_e32 v120, v87, v120
	v_add_f32_e32 v120, v88, v120
	v_add_f32_e32 v120, v89, v120
	v_cvt_pk_bf16_f32 v140, v84, v85
	v_cvt_pk_bf16_f32 v141, v86, v87
	ds_read_b64_tr_b16 v[206:207], v200 offset:30720
	ds_read_b64_tr_b16 v[208:209], v200 offset:31232
	v_mfma_f32_32x32x16_bf16 v[52:67], v[168:171], v[144:147], v[52:67]
	v_add_f32_e32 v84, v90, v120
	v_add_f32_e32 v84, v91, v84
	v_add_f32_e32 v84, v92, v84
	v_add_f32_e32 v84, v93, v84
	v_cvt_pk_bf16_f32 v142, v88, v89
	v_cvt_pk_bf16_f32 v143, v90, v91
	ds_read_b64_tr_b16 v[88:89], v200 offset:27648
	ds_read_b64_tr_b16 v[90:91], v200 offset:28160
	v_mfma_f32_32x32x16_bf16 v[68:83], v[172:175], v[136:139], v[68:83]
	v_add_f32_e32 v84, v94, v84
	v_add_f32_e32 v84, v95, v84
	v_add_f32_e32 v84, v96, v84
	v_add_f32_e32 v84, v97, v84
	v_cvt_pk_bf16_f32 v132, v92, v93
	v_cvt_pk_bf16_f32 v133, v94, v95
	ds_read_b64_tr_b16 v[92:93], v200 offset:31744
	ds_read_b64_tr_b16 v[94:95], v200 offset:32256
	v_mfma_f32_32x32x16_bf16 v[52:67], v[116:119], v[136:139], v[52:67]
	v_add_f32_e32 v84, v98, v84
	v_add_f32_e32 v200, v99, v84
	v_cvt_pk_bf16_f32 v134, v96, v97
	v_cvt_pk_bf16_f32 v135, v98, v99
	s_mov_b64 s[28:29], 0x10000
	s_add_i32 m0, s44, s59
	v_lshl_add_u64 v[84:85], v[0:1], 0, s[28:29]
	global_load_lds_dwordx4 v[84:85], off
	s_add_i32 m0, s25, s58
	v_lshl_add_u64 v[184:185], v[184:185], 0, s[36:37]
	global_load_lds_dwordx4 v[184:185], off
	s_waitcnt lgkmcnt(14)
	v_mfma_f32_32x32x16_bf16 v[4:19], v[152:155], v[196:199], v[4:19]
	v_exp_f32_e32 v68, v68
	v_exp_f32_e32 v69, v69
	v_exp_f32_e32 v70, v70
	v_exp_f32_e32 v71, v71
	s_waitcnt lgkmcnt(12)
	v_mfma_f32_32x32x16_bf16 v[20:35], v[152:155], v[100:103], v[20:35]
	v_exp_f32_e32 v72, v72
	v_exp_f32_e32 v73, v73
	v_exp_f32_e32 v74, v74
	v_exp_f32_e32 v75, v75
	v_add_u32_e32 v96, s25, v191
	ds_read_b128 v[84:87], v96
	ds_read_b128 v[168:171], v96 offset:512
	s_waitcnt lgkmcnt(12)
	v_mfma_f32_32x32x16_bf16 v[4:19], v[148:151], v[104:107], v[4:19]
	v_exp_f32_e32 v76, v76
	v_exp_f32_e32 v77, v77
	v_exp_f32_e32 v78, v78
	v_exp_f32_e32 v79, v79
	ds_read_b128 v[172:175], v96 offset:2048
	ds_read_b128 v[164:167], v96 offset:2560
	s_waitcnt lgkmcnt(12)
	v_mfma_f32_32x32x16_bf16 v[20:35], v[148:151], v[108:111], v[20:35]
	v_exp_f32_e32 v80, v80
	v_exp_f32_e32 v81, v81
	v_exp_f32_e32 v82, v82
	v_exp_f32_e32 v83, v83
	ds_read_b128 v[128:131], v96 offset:4096
	ds_read_b128 v[124:127], v96 offset:4608
	s_waitcnt lgkmcnt(12)
	v_mfma_f32_32x32x16_bf16 v[4:19], v[140:143], v[112:115], v[4:19]
	v_exp_f32_e32 v52, v52
	v_exp_f32_e32 v53, v53
	v_exp_f32_e32 v54, v54
	v_exp_f32_e32 v55, v55
	ds_read_b128 v[120:123], v96 offset:6144
	ds_read_b128 v[116:119], v96 offset:6656
	s_waitcnt lgkmcnt(12)
	v_mfma_f32_32x32x16_bf16 v[20:35], v[140:143], v[206:209], v[20:35]
	v_exp_f32_e32 v56, v56
	v_exp_f32_e32 v57, v57
	v_exp_f32_e32 v58, v58
	v_exp_f32_e32 v59, v59
	s_waitcnt lgkmcnt(10)
	v_mfma_f32_32x32x16_bf16 v[4:19], v[132:135], v[88:91], v[4:19]
	v_exp_f32_e32 v60, v60
	v_exp_f32_e32 v61, v61
	v_exp_f32_e32 v62, v62
	v_exp_f32_e32 v63, v63
	s_waitcnt lgkmcnt(8)
	v_mfma_f32_32x32x16_bf16 v[20:35], v[132:135], v[92:95], v[20:35]
	v_exp_f32_e32 v64, v64
	v_exp_f32_e32 v65, v65
	v_exp_f32_e32 v66, v66
	v_exp_f32_e32 v67, v67
	s_add_i32 s28, s25, 0x2000
	s_waitcnt vmcnt(2) lgkmcnt(0)
	s_barrier
	s_cmpk_lg_i32 s25, 0x4000
	v_add_f32_e32 v88, v192, v195
	s_cselect_b32 s29, s28, 0
	s_add_i32 s24, s24, 2
	v_add_f32_e32 v192, v88, v200
	v_lshl_add_u64 v[0:1], v[0:1], 0, s[36:37]
	s_cmpk_gt_u32 s24, 0xf8
	s_mov_b32 s45, s44
	s_cbranch_scc0 .LBB0_731
	s_and_b32 s24, s60, 0x3fffffc0
	s_cmp_lg_u32 0, -1
	s_cselect_b32 s28, 0, 0
	s_addk_i32 s28, 0x6000
	s_lshl_b32 s24, s24, 2
	v_add3_u32 v0, v194, s28, v193
	s_add_i32 s28, s24, 0
	v_add_u32_e32 v1, s44, v190
	ds_read_b64_tr_b16 v[194:195], v1 offset:24576
	ds_read_b64_tr_b16 v[196:197], v1 offset:25088
	v_add_f32_e32 v88, v68, v69
	v_add_f32_e32 v88, v70, v88
	v_add_f32_e32 v88, v71, v88
	v_add_f32_e32 v88, v72, v88
	v_add_f32_e32 v88, v73, v88
	v_cvt_pk_bf16_f32 v152, v68, v69
	v_cvt_pk_bf16_f32 v153, v70, v71
	s_waitcnt lgkmcnt(9)
	v_mfma_f32_32x32x16_bf16 v[100:115], v[84:87], v[160:163], v[36:51]
	ds_read_b64_tr_b16 v[68:69], v1 offset:28672
	ds_read_b64_tr_b16 v[70:71], v1 offset:29184
	v_add_f32_e32 v84, v74, v88
	v_add_f32_e32 v84, v75, v84
	v_add_f32_e32 v84, v76, v84
	v_add_f32_e32 v132, v77, v84
	v_cvt_pk_bf16_f32 v154, v72, v73
	v_cvt_pk_bf16_f32 v155, v74, v75
	s_waitcnt lgkmcnt(10)
	v_mfma_f32_32x32x16_bf16 v[84:99], v[168:171], v[160:163], v[36:51]
	ds_read_b64_tr_b16 v[72:73], v1 offset:25600
	ds_read_b64_tr_b16 v[74:75], v1 offset:26112
	v_add_f32_e32 v132, v78, v132
	v_add_f32_e32 v132, v79, v132
	v_add_f32_e32 v132, v80, v132
	v_add_f32_e32 v132, v81, v132
	v_cvt_pk_bf16_f32 v148, v76, v77
	v_cvt_pk_bf16_f32 v149, v78, v79
	s_waitcnt lgkmcnt(11)
	v_mfma_f32_32x32x16_bf16 v[100:115], v[172:175], v[156:159], v[100:115]
	ds_read_b64_tr_b16 v[76:77], v1 offset:29696
	ds_read_b64_tr_b16 v[78:79], v1 offset:30208
	v_add_f32_e32 v132, v82, v132
	v_add_f32_e32 v132, v83, v132
	v_add_f32_e32 v132, v52, v132
	v_add_f32_e32 v132, v53, v132
	v_cvt_pk_bf16_f32 v150, v80, v81
	v_cvt_pk_bf16_f32 v151, v82, v83
	s_waitcnt lgkmcnt(12)
	v_mfma_f32_32x32x16_bf16 v[84:99], v[164:167], v[156:159], v[84:99]
	ds_read_b64_tr_b16 v[80:81], v1 offset:26624
	ds_read_b64_tr_b16 v[82:83], v1 offset:27136
	s_waitcnt lgkmcnt(13)
	v_mfma_f32_32x32x16_bf16 v[100:115], v[128:131], v[144:147], v[100:115]
	v_add_f32_e32 v128, v54, v132
	v_add_f32_e32 v128, v55, v128
	v_add_f32_e32 v128, v56, v128
	v_add_f32_e32 v128, v57, v128
	v_cvt_pk_bf16_f32 v140, v52, v53
	v_cvt_pk_bf16_f32 v141, v54, v55
	ds_read_b64_tr_b16 v[52:53], v1 offset:30720
	ds_read_b64_tr_b16 v[54:55], v1 offset:31232
	s_waitcnt lgkmcnt(14)
	v_mfma_f32_32x32x16_bf16 v[84:99], v[124:127], v[144:147], v[84:99]
	v_add_f32_e32 v124, v58, v128
	v_add_f32_e32 v124, v59, v124
	v_add_f32_e32 v124, v60, v124
	v_add_f32_e32 v124, v61, v124
	v_cvt_pk_bf16_f32 v142, v56, v57
	v_cvt_pk_bf16_f32 v143, v58, v59
	ds_read_b64_tr_b16 v[56:57], v1 offset:27648
	ds_read_b64_tr_b16 v[58:59], v1 offset:28160
	s_waitcnt lgkmcnt(14)
	v_mfma_f32_32x32x16_bf16 v[100:115], v[120:123], v[136:139], v[100:115]
	v_add_f32_e32 v120, v62, v124
	v_add_f32_e32 v120, v63, v120
	v_add_f32_e32 v120, v64, v120
	v_add_f32_e32 v120, v65, v120
	v_cvt_pk_bf16_f32 v132, v60, v61
	v_cvt_pk_bf16_f32 v133, v62, v63
	ds_read_b64_tr_b16 v[60:61], v1 offset:31744
	ds_read_b64_tr_b16 v[62:63], v1 offset:32256
	v_add_f32_e32 v1, v66, v120
	v_add_f32_e32 v1, v67, v1
	v_add_f32_e32 v1, 0, v1
	v_cvt_pk_bf16_f32 v134, v64, v65
	v_cvt_pk_bf16_f32 v135, v66, v67
	v_mfma_f32_32x32x16_bf16 v[84:99], v[116:119], v[136:139], v[84:99]
	s_mov_b64 s[46:47], 0x3f8000
	s_add_i32 s24, s25, s59
	v_lshl_add_u64 v[64:65], v[182:183], 0, s[46:47]
	s_mov_b32 s44, m0
	s_mov_b32 m0, s24
	s_nop 0
	global_load_lds_dwordx4 v[64:65], off
	s_mov_b32 m0, s44
	s_mov_b64 s[44:45], 0x3f0000
	v_lshl_add_u64 v[64:65], v[180:181], 0, s[44:45]
	s_add_i32 s24, s29, s58
	s_mov_b32 s44, m0
	s_mov_b32 m0, s24
	s_nop 0
	global_load_lds_dwordx4 v[64:65], off
	s_mov_b32 m0, s44
	v_add_f32_e32 v1, v192, v1
	s_waitcnt lgkmcnt(14)
	v_mfma_f32_32x32x16_bf16 v[4:19], v[152:155], v[194:197], v[4:19]
	v_exp_f32_e32 v100, v100
	v_exp_f32_e32 v101, v101
	v_exp_f32_e32 v102, v102
	v_exp_f32_e32 v103, v103
	s_waitcnt lgkmcnt(12)
	v_mfma_f32_32x32x16_bf16 v[20:35], v[152:155], v[68:71], v[20:35]
	v_exp_f32_e32 v104, v104
	v_exp_f32_e32 v105, v105
	v_exp_f32_e32 v106, v106
	v_exp_f32_e32 v107, v107
	v_add_u32_e32 v68, s29, v191
	ds_read_b128 v[64:67], v68
	ds_read_b128 v[164:167], v68 offset:512
	s_waitcnt lgkmcnt(12)
	v_mfma_f32_32x32x16_bf16 v[4:19], v[148:151], v[72:75], v[4:19]
	v_exp_f32_e32 v108, v108
	v_exp_f32_e32 v109, v109
	v_exp_f32_e32 v110, v110
	v_exp_f32_e32 v111, v111
	ds_read_b128 v[72:75], v68 offset:2048
	ds_read_b128 v[168:171], v68 offset:2560
	s_waitcnt lgkmcnt(12)
	v_mfma_f32_32x32x16_bf16 v[20:35], v[148:151], v[76:79], v[20:35]
	v_exp_f32_e32 v112, v112
	v_exp_f32_e32 v113, v113
	v_exp_f32_e32 v114, v114
	v_exp_f32_e32 v115, v115
	ds_read_b128 v[76:79], v68 offset:4096
	ds_read_b128 v[172:175], v68 offset:4608
	s_waitcnt lgkmcnt(12)
	v_mfma_f32_32x32x16_bf16 v[4:19], v[140:143], v[80:83], v[4:19]
	v_exp_f32_e32 v84, v84
	v_exp_f32_e32 v85, v85
	v_exp_f32_e32 v86, v86
	v_exp_f32_e32 v87, v87
	ds_read_b128 v[80:83], v68 offset:6144
	ds_read_b128 v[68:71], v68 offset:6656
	s_waitcnt lgkmcnt(12)
	v_mfma_f32_32x32x16_bf16 v[20:35], v[140:143], v[52:55], v[20:35]
	v_exp_f32_e32 v88, v88
	v_exp_f32_e32 v89, v89
	v_exp_f32_e32 v90, v90
	v_exp_f32_e32 v91, v91
	s_waitcnt lgkmcnt(10)
	v_mfma_f32_32x32x16_bf16 v[4:19], v[132:135], v[56:59], v[4:19]
	v_exp_f32_e32 v92, v92
	v_exp_f32_e32 v93, v93
	v_exp_f32_e32 v94, v94
	v_exp_f32_e32 v95, v95
	s_waitcnt lgkmcnt(8)
	v_mfma_f32_32x32x16_bf16 v[20:35], v[132:135], v[60:63], v[20:35]
	v_exp_f32_e32 v96, v96
	v_exp_f32_e32 v97, v97
	v_exp_f32_e32 v98, v98
	v_exp_f32_e32 v99, v99
	s_waitcnt vmcnt(2) lgkmcnt(0)
	s_barrier
	s_add_i32 s24, s29, 0x2000
	s_cmpk_lg_i32 s29, 0x4000
	s_cselect_b32 s44, s24, 0
	v_add_u32_e32 v184, s25, v190
	ds_read_b64_tr_b16 v[192:193], v184 offset:24576
	ds_read_b64_tr_b16 v[194:195], v184 offset:25088
	v_add_f32_e32 v52, v100, v101
	v_add_f32_e32 v52, v102, v52
	v_add_f32_e32 v52, v103, v52
	v_add_f32_e32 v52, v104, v52
	v_add_f32_e32 v52, v105, v52
	v_cvt_pk_bf16_f32 v152, v100, v101
	v_cvt_pk_bf16_f32 v153, v102, v103
	s_waitcnt lgkmcnt(9)
	v_mfma_f32_32x32x16_bf16 v[116:131], v[64:67], v[160:163], v[36:51]
	ds_read_b64_tr_b16 v[100:101], v184 offset:28672
	ds_read_b64_tr_b16 v[102:103], v184 offset:29184
	v_add_f32_e32 v52, v106, v52
	v_add_f32_e32 v52, v107, v52
	v_add_f32_e32 v52, v108, v52
	v_add_f32_e32 v132, v109, v52
	v_cvt_pk_bf16_f32 v154, v104, v105
	v_cvt_pk_bf16_f32 v155, v106, v107
	s_waitcnt lgkmcnt(10)
	v_mfma_f32_32x32x16_bf16 v[52:67], v[164:167], v[160:163], v[36:51]
	ds_read_b64_tr_b16 v[104:105], v184 offset:25600
	ds_read_b64_tr_b16 v[106:107], v184 offset:26112
	s_waitcnt lgkmcnt(11)
	v_mfma_f32_32x32x16_bf16 v[116:131], v[72:75], v[156:159], v[116:131]
	v_add_f32_e32 v72, v110, v132
	v_add_f32_e32 v72, v111, v72
	v_add_f32_e32 v72, v112, v72
	v_add_f32_e32 v132, v113, v72
	v_cvt_pk_bf16_f32 v148, v108, v109
	v_cvt_pk_bf16_f32 v149, v110, v111
	ds_read_b64_tr_b16 v[72:73], v184 offset:29696
	ds_read_b64_tr_b16 v[74:75], v184 offset:30208
	v_add_f32_e32 v108, v114, v132
	v_add_f32_e32 v108, v115, v108
	v_add_f32_e32 v108, v84, v108
	v_add_f32_e32 v132, v85, v108
	v_cvt_pk_bf16_f32 v150, v112, v113
	v_cvt_pk_bf16_f32 v151, v114, v115
	s_waitcnt lgkmcnt(12)
	v_mfma_f32_32x32x16_bf16 v[52:67], v[168:171], v[156:159], v[52:67]
	ds_read_b64_tr_b16 v[108:109], v184 offset:26624
	ds_read_b64_tr_b16 v[110:111], v184 offset:27136
	s_waitcnt lgkmcnt(13)
	v_mfma_f32_32x32x16_bf16 v[116:131], v[76:79], v[144:147], v[116:131]
	v_add_f32_e32 v76, v86, v132
	v_add_f32_e32 v76, v87, v76
	v_add_f32_e32 v76, v88, v76
	v_add_f32_e32 v112, v89, v76
	v_cvt_pk_bf16_f32 v140, v84, v85
	v_cvt_pk_bf16_f32 v141, v86, v87
	ds_read_b64_tr_b16 v[76:77], v184 offset:30720
	ds_read_b64_tr_b16 v[78:79], v184 offset:31232
	v_add_f32_e32 v84, v90, v112
	v_add_f32_e32 v84, v91, v84
	v_add_f32_e32 v84, v92, v84
	v_add_f32_e32 v84, v93, v84
	v_cvt_pk_bf16_f32 v142, v88, v89
	v_cvt_pk_bf16_f32 v143, v90, v91
	s_waitcnt lgkmcnt(14)
	v_mfma_f32_32x32x16_bf16 v[52:67], v[172:175], v[144:147], v[52:67]
	ds_read_b64_tr_b16 v[88:89], v184 offset:27648
	ds_read_b64_tr_b16 v[90:91], v184 offset:28160
	s_waitcnt lgkmcnt(14)
	v_mfma_f32_32x32x16_bf16 v[116:131], v[80:83], v[136:139], v[116:131]
	v_add_f32_e32 v80, v94, v84
	v_add_f32_e32 v80, v95, v80
	v_add_f32_e32 v80, v96, v80
	v_add_f32_e32 v84, v97, v80
	v_cvt_pk_bf16_f32 v132, v92, v93
	v_cvt_pk_bf16_f32 v133, v94, v95
	ds_read_b64_tr_b16 v[80:81], v184 offset:31744
	ds_read_b64_tr_b16 v[82:83], v184 offset:32256
	v_mfma_f32_32x32x16_bf16 v[52:67], v[68:71], v[136:139], v[52:67]
	v_add_f32_e32 v68, v98, v84
	v_add_f32_e32 v68, v99, v68
	v_add_f32_e32 v68, 0, v68
	v_cvt_pk_bf16_f32 v134, v96, v97
	v_cvt_pk_bf16_f32 v135, v98, v99
	s_mov_b64 s[60:61], 0x3fc000
	v_add_f32_e32 v1, v1, v68
	s_add_i32 s24, s29, s59
	v_lshl_add_u64 v[68:69], v[182:183], 0, s[60:61]
	s_mov_b32 s25, m0
	s_mov_b32 m0, s24
	s_nop 0
	global_load_lds_dwordx4 v[68:69], off
	s_mov_b32 m0, s25
	s_mov_b64 s[24:25], 0x3f4000
	s_add_i32 s45, s44, s58
	v_lshl_add_u64 v[68:69], v[180:181], 0, s[24:25]
	s_mov_b32 s24, m0
	s_mov_b32 m0, s45
	s_nop 0
	global_load_lds_dwordx4 v[68:69], off
	s_mov_b32 m0, s24
	s_waitcnt lgkmcnt(14)
	v_mfma_f32_32x32x16_bf16 v[4:19], v[152:155], v[192:195], v[4:19]
	v_exp_f32_e32 v116, v116
	v_exp_f32_e32 v117, v117
	v_exp_f32_e32 v118, v118
	v_exp_f32_e32 v119, v119
	s_waitcnt lgkmcnt(12)
	v_mfma_f32_32x32x16_bf16 v[20:35], v[152:155], v[100:103], v[20:35]
	v_exp_f32_e32 v120, v120
	v_exp_f32_e32 v121, v121
	v_exp_f32_e32 v122, v122
	v_exp_f32_e32 v123, v123
	v_add_u32_e32 v84, s44, v191
	ds_read_b128 v[68:71], v84
	ds_read_b128 v[92:95], v84 offset:512
	s_waitcnt lgkmcnt(12)
	v_mfma_f32_32x32x16_bf16 v[4:19], v[148:151], v[104:107], v[4:19]
	v_exp_f32_e32 v124, v124
	v_exp_f32_e32 v125, v125
	v_exp_f32_e32 v126, v126
	v_exp_f32_e32 v127, v127
	ds_read_b128 v[96:99], v84 offset:2048
	ds_read_b128 v[164:167], v84 offset:2560
	s_waitcnt lgkmcnt(12)
	v_mfma_f32_32x32x16_bf16 v[20:35], v[148:151], v[72:75], v[20:35]
	v_exp_f32_e32 v128, v128
	v_exp_f32_e32 v129, v129
	v_exp_f32_e32 v130, v130
	v_exp_f32_e32 v131, v131
	ds_read_b128 v[168:171], v84 offset:4096
	ds_read_b128 v[172:175], v84 offset:4608
	s_waitcnt lgkmcnt(12)
	v_mfma_f32_32x32x16_bf16 v[4:19], v[140:143], v[108:111], v[4:19]
	v_exp_f32_e32 v52, v52
	v_exp_f32_e32 v53, v53
	v_exp_f32_e32 v54, v54
	v_exp_f32_e32 v55, v55
	ds_read_b128 v[182:185], v84 offset:6144
	ds_read_b128 v[84:87], v84 offset:6656
	s_waitcnt lgkmcnt(12)
	v_mfma_f32_32x32x16_bf16 v[20:35], v[140:143], v[76:79], v[20:35]
	v_exp_f32_e32 v56, v56
	v_exp_f32_e32 v57, v57
	v_exp_f32_e32 v58, v58
	v_exp_f32_e32 v59, v59
	s_waitcnt lgkmcnt(10)
	v_mfma_f32_32x32x16_bf16 v[4:19], v[132:135], v[88:91], v[4:19]
	v_exp_f32_e32 v60, v60
	v_exp_f32_e32 v61, v61
	v_exp_f32_e32 v62, v62
	v_exp_f32_e32 v63, v63
	s_waitcnt lgkmcnt(8)
	v_mfma_f32_32x32x16_bf16 v[20:35], v[132:135], v[80:83], v[20:35]
	v_exp_f32_e32 v64, v64
	v_exp_f32_e32 v65, v65
	v_exp_f32_e32 v66, v66
	v_exp_f32_e32 v67, v67
	s_waitcnt vmcnt(2) lgkmcnt(0)
	s_barrier
	s_add_i32 s24, s44, 0x2000
	s_cmpk_lg_i32 s44, 0x4000
	s_cselect_b32 s25, s24, 0
	v_add_u32_e32 v192, s29, v190
	ds_read_b64_tr_b16 v[88:89], v192 offset:24576
	ds_read_b64_tr_b16 v[90:91], v192 offset:25088
	v_add_f32_e32 v72, v116, v117
	v_add_f32_e32 v72, v118, v72
	v_add_f32_e32 v72, v119, v72
	v_add_f32_e32 v72, v120, v72
	v_add_f32_e32 v72, v121, v72
	v_cvt_pk_bf16_f32 v152, v116, v117
	v_cvt_pk_bf16_f32 v153, v118, v119
	s_waitcnt lgkmcnt(9)
	v_mfma_f32_32x32x16_bf16 v[100:115], v[68:71], v[160:163], v[36:51]
	ds_read_b64_tr_b16 v[116:117], v192 offset:28672
	ds_read_b64_tr_b16 v[118:119], v192 offset:29184
	v_add_f32_e32 v68, v122, v72
	v_add_f32_e32 v68, v123, v68
	v_add_f32_e32 v68, v124, v68
	v_add_f32_e32 v132, v125, v68
	v_cvt_pk_bf16_f32 v154, v120, v121
	v_cvt_pk_bf16_f32 v155, v122, v123
	s_waitcnt lgkmcnt(10)
	v_mfma_f32_32x32x16_bf16 v[68:83], v[92:95], v[160:163], v[36:51]
	ds_read_b64_tr_b16 v[92:93], v192 offset:25600
	ds_read_b64_tr_b16 v[94:95], v192 offset:26112
	s_waitcnt lgkmcnt(11)
	v_mfma_f32_32x32x16_bf16 v[100:115], v[96:99], v[156:159], v[100:115]
	v_add_f32_e32 v96, v126, v132
	v_add_f32_e32 v96, v127, v96
	v_add_f32_e32 v96, v128, v96
	v_add_f32_e32 v120, v129, v96
	v_cvt_pk_bf16_f32 v148, v124, v125
	v_cvt_pk_bf16_f32 v149, v126, v127
	ds_read_b64_tr_b16 v[96:97], v192 offset:29696
	ds_read_b64_tr_b16 v[98:99], v192 offset:30208
	v_add_f32_e32 v120, v130, v120
	v_add_f32_e32 v120, v131, v120
	v_add_f32_e32 v120, v52, v120
	v_add_f32_e32 v124, v53, v120
	v_cvt_pk_bf16_f32 v150, v128, v129
	v_cvt_pk_bf16_f32 v151, v130, v131
	s_waitcnt lgkmcnt(12)
	v_mfma_f32_32x32x16_bf16 v[68:83], v[164:167], v[156:159], v[68:83]
	ds_read_b64_tr_b16 v[120:121], v192 offset:26624
	ds_read_b64_tr_b16 v[122:123], v192 offset:27136
	v_add_f32_e32 v124, v54, v124
	v_add_f32_e32 v124, v55, v124
	v_add_f32_e32 v124, v56, v124
	v_add_f32_e32 v124, v57, v124
	v_cvt_pk_bf16_f32 v140, v52, v53
	v_cvt_pk_bf16_f32 v141, v54, v55
	s_waitcnt lgkmcnt(13)
	v_mfma_f32_32x32x16_bf16 v[100:115], v[168:171], v[144:147], v[100:115]
	ds_read_b64_tr_b16 v[52:53], v192 offset:30720
	ds_read_b64_tr_b16 v[54:55], v192 offset:31232
	v_add_f32_e32 v124, v58, v124
	v_add_f32_e32 v124, v59, v124
	v_add_f32_e32 v124, v60, v124
	v_add_f32_e32 v124, v61, v124
	v_cvt_pk_bf16_f32 v142, v56, v57
	v_cvt_pk_bf16_f32 v143, v58, v59
	s_waitcnt lgkmcnt(14)
	v_mfma_f32_32x32x16_bf16 v[68:83], v[172:175], v[144:147], v[68:83]
	ds_read_b64_tr_b16 v[56:57], v192 offset:27648
	ds_read_b64_tr_b16 v[58:59], v192 offset:28160
	v_add_f32_e32 v124, v62, v124
	v_add_f32_e32 v124, v63, v124
	v_add_f32_e32 v124, v64, v124
	v_add_f32_e32 v124, v65, v124
	v_cvt_pk_bf16_f32 v132, v60, v61
	v_cvt_pk_bf16_f32 v133, v62, v63
	s_waitcnt lgkmcnt(14)
	v_mfma_f32_32x32x16_bf16 v[100:115], v[182:185], v[136:139], v[100:115]
	ds_read_b64_tr_b16 v[60:61], v192 offset:31744
	ds_read_b64_tr_b16 v[62:63], v192 offset:32256
	v_mfma_f32_32x32x16_bf16 v[68:83], v[84:87], v[136:139], v[68:83]
	v_add_f32_e32 v84, v66, v124
	v_add_f32_e32 v84, v67, v84
	v_add_f32_e32 v84, 0, v84
	v_cvt_pk_bf16_f32 v134, v64, v65
	v_cvt_pk_bf16_f32 v135, v66, v67
	v_lshl_add_u64 v[64:65], v[180:181], 0, s[46:47]
	s_add_i32 s24, s25, s58
	s_mov_b32 s29, m0
	s_mov_b32 m0, s24
	s_nop 0
	global_load_lds_dwordx4 v[64:65], off
	s_mov_b32 m0, s29
	v_add_f32_e32 v1, v1, v84
	s_waitcnt lgkmcnt(14)
	v_mfma_f32_32x32x16_bf16 v[4:19], v[152:155], v[88:91], v[4:19]
	v_exp_f32_e32 v100, v100
	v_exp_f32_e32 v101, v101
	v_exp_f32_e32 v102, v102
	v_exp_f32_e32 v103, v103
	s_waitcnt lgkmcnt(12)
	v_mfma_f32_32x32x16_bf16 v[20:35], v[152:155], v[116:119], v[20:35]
	v_exp_f32_e32 v104, v104
	v_exp_f32_e32 v105, v105
	v_exp_f32_e32 v106, v106
	v_exp_f32_e32 v107, v107
	v_add_u32_e32 v84, s25, v191
	ds_read_b128 v[64:67], v84
	ds_read_b128 v[124:127], v84 offset:512
	s_waitcnt lgkmcnt(12)
	v_mfma_f32_32x32x16_bf16 v[4:19], v[148:151], v[92:95], v[4:19]
	v_exp_f32_e32 v108, v108
	v_exp_f32_e32 v109, v109
	v_exp_f32_e32 v110, v110
	v_exp_f32_e32 v111, v111
	ds_read_b128 v[128:131], v84 offset:2048
	ds_read_b128 v[164:167], v84 offset:2560
	s_waitcnt lgkmcnt(12)
	v_mfma_f32_32x32x16_bf16 v[20:35], v[148:151], v[96:99], v[20:35]
	v_exp_f32_e32 v112, v112
	v_exp_f32_e32 v113, v113
	v_exp_f32_e32 v114, v114
	v_exp_f32_e32 v115, v115
	ds_read_b128 v[168:171], v84 offset:4096
	ds_read_b128 v[172:175], v84 offset:4608
	s_waitcnt lgkmcnt(12)
	v_mfma_f32_32x32x16_bf16 v[4:19], v[140:143], v[120:123], v[4:19]
	v_exp_f32_e32 v68, v68
	v_exp_f32_e32 v69, v69
	v_exp_f32_e32 v70, v70
	v_exp_f32_e32 v71, v71
	ds_read_b128 v[120:123], v84 offset:6144
	ds_read_b128 v[116:119], v84 offset:6656
	s_waitcnt lgkmcnt(12)
	v_mfma_f32_32x32x16_bf16 v[20:35], v[140:143], v[52:55], v[20:35]
	v_exp_f32_e32 v72, v72
	v_exp_f32_e32 v73, v73
	v_exp_f32_e32 v74, v74
	v_exp_f32_e32 v75, v75
	s_waitcnt lgkmcnt(10)
	v_mfma_f32_32x32x16_bf16 v[4:19], v[132:135], v[56:59], v[4:19]
	v_exp_f32_e32 v76, v76
	v_exp_f32_e32 v77, v77
	v_exp_f32_e32 v78, v78
	v_exp_f32_e32 v79, v79
	s_waitcnt lgkmcnt(8)
	v_mfma_f32_32x32x16_bf16 v[20:35], v[132:135], v[60:63], v[20:35]
	v_exp_f32_e32 v80, v80
	v_exp_f32_e32 v81, v81
	v_exp_f32_e32 v82, v82
	v_exp_f32_e32 v83, v83
	s_waitcnt vmcnt(1) lgkmcnt(0)
	s_barrier
	s_add_i32 s24, s25, 0x2000
	s_cmpk_lg_i32 s25, 0x4000
	s_cselect_b32 s24, s24, 0
	v_add_u32_e32 v192, s44, v190
	ds_read_b64_tr_b16 v[182:183], v192 offset:24576
	ds_read_b64_tr_b16 v[184:185], v192 offset:25088
	v_add_f32_e32 v52, v100, v101
	v_add_f32_e32 v52, v102, v52
	v_add_f32_e32 v52, v103, v52
	v_add_f32_e32 v52, v104, v52
	v_add_f32_e32 v52, v105, v52
	v_cvt_pk_bf16_f32 v152, v100, v101
	v_cvt_pk_bf16_f32 v153, v102, v103
	s_waitcnt lgkmcnt(9)
	v_mfma_f32_32x32x16_bf16 v[84:99], v[64:67], v[160:163], v[36:51]
	ds_read_b64_tr_b16 v[100:101], v192 offset:28672
	ds_read_b64_tr_b16 v[102:103], v192 offset:29184
	v_add_f32_e32 v52, v106, v52
	v_add_f32_e32 v52, v107, v52
	v_add_f32_e32 v52, v108, v52
	v_add_f32_e32 v132, v109, v52
	v_cvt_pk_bf16_f32 v154, v104, v105
	v_cvt_pk_bf16_f32 v155, v106, v107
	s_waitcnt lgkmcnt(10)
	v_mfma_f32_32x32x16_bf16 v[52:67], v[124:127], v[160:163], v[36:51]
	ds_read_b64_tr_b16 v[104:105], v192 offset:25600
	ds_read_b64_tr_b16 v[106:107], v192 offset:26112
	v_add_f32_e32 v124, v110, v132
	v_add_f32_e32 v124, v111, v124
	v_add_f32_e32 v124, v112, v124
	v_add_f32_e32 v124, v113, v124
	v_cvt_pk_bf16_f32 v148, v108, v109
	v_cvt_pk_bf16_f32 v149, v110, v111
	s_waitcnt lgkmcnt(11)
	v_mfma_f32_32x32x16_bf16 v[84:99], v[128:131], v[156:159], v[84:99]
	ds_read_b64_tr_b16 v[108:109], v192 offset:29696
	ds_read_b64_tr_b16 v[110:111], v192 offset:30208
	v_add_f32_e32 v124, v114, v124
	v_add_f32_e32 v124, v115, v124
	v_add_f32_e32 v124, v68, v124
	v_add_f32_e32 v124, v69, v124
	v_cvt_pk_bf16_f32 v150, v112, v113
	v_cvt_pk_bf16_f32 v151, v114, v115
	s_waitcnt lgkmcnt(12)
	v_mfma_f32_32x32x16_bf16 v[52:67], v[164:167], v[156:159], v[52:67]
	ds_read_b64_tr_b16 v[112:113], v192 offset:26624
	ds_read_b64_tr_b16 v[114:115], v192 offset:27136
	v_add_f32_e32 v124, v70, v124
	v_add_f32_e32 v124, v71, v124
	v_add_f32_e32 v124, v72, v124
	v_add_f32_e32 v124, v73, v124
	v_cvt_pk_bf16_f32 v140, v68, v69
	v_cvt_pk_bf16_f32 v141, v70, v71
	s_waitcnt lgkmcnt(13)
	v_mfma_f32_32x32x16_bf16 v[84:99], v[168:171], v[144:147], v[84:99]
	ds_read_b64_tr_b16 v[68:69], v192 offset:30720
	ds_read_b64_tr_b16 v[70:71], v192 offset:31232
	v_add_f32_e32 v124, v74, v124
	v_add_f32_e32 v124, v75, v124
	v_add_f32_e32 v124, v76, v124
	v_add_f32_e32 v124, v77, v124
	v_cvt_pk_bf16_f32 v142, v72, v73
	v_cvt_pk_bf16_f32 v143, v74, v75
	s_waitcnt lgkmcnt(14)
	v_mfma_f32_32x32x16_bf16 v[52:67], v[172:175], v[144:147], v[52:67]
	ds_read_b64_tr_b16 v[72:73], v192 offset:27648
	ds_read_b64_tr_b16 v[74:75], v192 offset:28160
	s_waitcnt lgkmcnt(14)
	v_mfma_f32_32x32x16_bf16 v[84:99], v[120:123], v[136:139], v[84:99]
	v_add_f32_e32 v120, v78, v124
	v_add_f32_e32 v120, v79, v120
	v_add_f32_e32 v120, v80, v120
	v_add_f32_e32 v120, v81, v120
	v_cvt_pk_bf16_f32 v132, v76, v77
	v_cvt_pk_bf16_f32 v133, v78, v79
	ds_read_b64_tr_b16 v[76:77], v192 offset:31744
	ds_read_b64_tr_b16 v[78:79], v192 offset:32256
	v_mfma_f32_32x32x16_bf16 v[52:67], v[116:119], v[136:139], v[52:67]
	v_add_f32_e32 v116, v82, v120
	v_add_f32_e32 v116, v83, v116
	v_add_f32_e32 v116, 0, v116
	v_cvt_pk_bf16_f32 v134, v80, v81
	v_cvt_pk_bf16_f32 v135, v82, v83
	s_add_i32 s29, s24, s58
	v_lshl_add_u64 v[80:81], v[180:181], 0, s[60:61]
	s_mov_b32 s44, m0
	s_mov_b32 m0, s29
	s_nop 0
	global_load_lds_dwordx4 v[80:81], off
	s_mov_b32 m0, s44
	v_add_f32_e32 v1, v1, v116
	s_waitcnt lgkmcnt(14)
	v_mfma_f32_32x32x16_bf16 v[4:19], v[152:155], v[182:185], v[4:19]
	v_exp_f32_e32 v84, v84
	v_exp_f32_e32 v85, v85
	v_exp_f32_e32 v86, v86
	v_exp_f32_e32 v87, v87
	s_waitcnt lgkmcnt(12)
	v_mfma_f32_32x32x16_bf16 v[20:35], v[152:155], v[100:103], v[20:35]
	v_exp_f32_e32 v88, v88
	v_exp_f32_e32 v89, v89
	v_exp_f32_e32 v90, v90
	v_exp_f32_e32 v91, v91
	v_add_u32_e32 v80, s24, v191
	ds_read_b128 v[116:119], v80
	ds_read_b128 v[120:123], v80 offset:512
	s_waitcnt lgkmcnt(12)
	v_mfma_f32_32x32x16_bf16 v[4:19], v[148:151], v[104:107], v[4:19]
	v_exp_f32_e32 v92, v92
	v_exp_f32_e32 v93, v93
	v_exp_f32_e32 v94, v94
	v_exp_f32_e32 v95, v95
	ds_read_b128 v[104:107], v80 offset:2048
	ds_read_b128 v[124:127], v80 offset:2560
	s_waitcnt lgkmcnt(12)
	v_mfma_f32_32x32x16_bf16 v[20:35], v[148:151], v[108:111], v[20:35]
	v_exp_f32_e32 v96, v96
	v_exp_f32_e32 v97, v97
	v_exp_f32_e32 v98, v98
	v_exp_f32_e32 v99, v99
	ds_read_b128 v[108:111], v80 offset:4096
	ds_read_b128 v[128:131], v80 offset:4608
	s_waitcnt lgkmcnt(12)
	v_mfma_f32_32x32x16_bf16 v[4:19], v[140:143], v[112:115], v[4:19]
	v_exp_f32_e32 v52, v52
	v_exp_f32_e32 v53, v53
	v_exp_f32_e32 v54, v54
	v_exp_f32_e32 v55, v55
	ds_read_b128 v[112:115], v80 offset:6144
	ds_read_b128 v[100:103], v80 offset:6656
	s_waitcnt lgkmcnt(12)
	v_mfma_f32_32x32x16_bf16 v[20:35], v[140:143], v[68:71], v[20:35]
	v_exp_f32_e32 v56, v56
	v_exp_f32_e32 v57, v57
	v_exp_f32_e32 v58, v58
	v_exp_f32_e32 v59, v59
	s_waitcnt lgkmcnt(10)
	v_mfma_f32_32x32x16_bf16 v[4:19], v[132:135], v[72:75], v[4:19]
	v_exp_f32_e32 v60, v60
	v_exp_f32_e32 v61, v61
	v_exp_f32_e32 v62, v62
	v_exp_f32_e32 v63, v63
	s_waitcnt lgkmcnt(8)
	v_mfma_f32_32x32x16_bf16 v[20:35], v[132:135], v[76:79], v[20:35]
	v_exp_f32_e32 v64, v64
	v_exp_f32_e32 v65, v65
	v_exp_f32_e32 v66, v66
	v_exp_f32_e32 v67, v67
	s_waitcnt vmcnt(0) lgkmcnt(0)
	s_barrier
	v_add_u32_e32 v168, s25, v190
	ds_read_b64_tr_b16 v[164:165], v168 offset:24576
	ds_read_b64_tr_b16 v[166:167], v168 offset:25088
	v_add_f32_e32 v68, v84, v85
	v_add_f32_e32 v68, v86, v68
	v_add_f32_e32 v68, v87, v68
	v_add_f32_e32 v68, v88, v68
	v_add_f32_e32 v132, v89, v68
	v_cvt_pk_bf16_f32 v152, v84, v85
	v_cvt_pk_bf16_f32 v153, v86, v87
	s_waitcnt lgkmcnt(9)
	v_mfma_f32_32x32x16_bf16 v[68:83], v[116:119], v[160:163], v[36:51]
	ds_read_b64_tr_b16 v[84:85], v168 offset:28672
	ds_read_b64_tr_b16 v[86:87], v168 offset:29184
	v_add_f32_e32 v116, v90, v132
	v_add_f32_e32 v116, v91, v116
	v_add_f32_e32 v116, v92, v116
	v_add_f32_e32 v116, v93, v116
	v_cvt_pk_bf16_f32 v154, v88, v89
	v_cvt_pk_bf16_f32 v155, v90, v91
	s_waitcnt lgkmcnt(10)
	v_mfma_f32_32x32x16_bf16 v[36:51], v[120:123], v[160:163], v[36:51]
	ds_read_b64_tr_b16 v[88:89], v168 offset:25600
	ds_read_b64_tr_b16 v[90:91], v168 offset:26112
	s_waitcnt lgkmcnt(11)
	v_mfma_f32_32x32x16_bf16 v[68:83], v[104:107], v[156:159], v[68:83]
	v_add_f32_e32 v104, v94, v116
	v_add_f32_e32 v104, v95, v104
	v_add_f32_e32 v104, v96, v104
	v_add_f32_e32 v104, v97, v104
	v_cvt_pk_bf16_f32 v148, v92, v93
	v_cvt_pk_bf16_f32 v149, v94, v95
	ds_read_b64_tr_b16 v[92:93], v168 offset:29696
	ds_read_b64_tr_b16 v[94:95], v168 offset:30208
	v_add_f32_e32 v104, v98, v104
	v_add_f32_e32 v104, v99, v104
	v_add_f32_e32 v104, v52, v104
	v_add_f32_e32 v104, v53, v104
	v_cvt_pk_bf16_f32 v150, v96, v97
	v_cvt_pk_bf16_f32 v151, v98, v99
	s_waitcnt lgkmcnt(12)
	v_mfma_f32_32x32x16_bf16 v[36:51], v[124:127], v[156:159], v[36:51]
	ds_read_b64_tr_b16 v[96:97], v168 offset:26624
	ds_read_b64_tr_b16 v[98:99], v168 offset:27136
	v_add_f32_e32 v104, v54, v104
	v_add_f32_e32 v104, v55, v104
	v_add_f32_e32 v104, v56, v104
	v_add_f32_e32 v104, v57, v104
	v_cvt_pk_bf16_f32 v140, v52, v53
	v_cvt_pk_bf16_f32 v141, v54, v55
	s_waitcnt lgkmcnt(13)
	v_mfma_f32_32x32x16_bf16 v[68:83], v[108:111], v[144:147], v[68:83]
	ds_read_b64_tr_b16 v[52:53], v168 offset:30720
	ds_read_b64_tr_b16 v[54:55], v168 offset:31232
	v_add_f32_e32 v104, v58, v104
	v_add_f32_e32 v104, v59, v104
	v_add_f32_e32 v104, v60, v104
	v_add_f32_e32 v104, v61, v104
	v_cvt_pk_bf16_f32 v142, v56, v57
	v_cvt_pk_bf16_f32 v143, v58, v59
	s_waitcnt lgkmcnt(14)
	v_mfma_f32_32x32x16_bf16 v[36:51], v[128:131], v[144:147], v[36:51]
	ds_read_b64_tr_b16 v[56:57], v168 offset:27648
	ds_read_b64_tr_b16 v[58:59], v168 offset:28160
	v_add_f32_e32 v104, v62, v104
	v_add_f32_e32 v104, v63, v104
	v_add_f32_e32 v104, v64, v104
	v_add_f32_e32 v104, v65, v104
	v_cvt_pk_bf16_f32 v132, v60, v61
	v_cvt_pk_bf16_f32 v133, v62, v63
	s_waitcnt lgkmcnt(14)
	v_mfma_f32_32x32x16_bf16 v[68:83], v[112:115], v[136:139], v[68:83]
	ds_read_b64_tr_b16 v[60:61], v168 offset:31744
	ds_read_b64_tr_b16 v[62:63], v168 offset:32256
	v_mfma_f32_32x32x16_bf16 v[36:51], v[100:103], v[136:139], v[36:51]
	v_add_f32_e32 v100, v66, v104
	v_add_f32_e32 v100, v67, v100
	v_add_f32_e32 v100, 0, v100
	v_cvt_pk_bf16_f32 v134, v64, v65
	v_cvt_pk_bf16_f32 v135, v66, v67
	s_waitcnt lgkmcnt(14)
	v_mfma_f32_32x32x16_bf16 v[4:19], v[152:155], v[164:167], v[4:19]
	s_nop 1
	v_exp_f32_e32 v68, v68
	v_exp_f32_e32 v69, v69
	v_exp_f32_e32 v70, v70
	v_exp_f32_e32 v71, v71
	s_waitcnt lgkmcnt(12)
	v_mfma_f32_32x32x16_bf16 v[20:35], v[152:155], v[84:87], v[20:35]
	v_exp_f32_e32 v72, v72
	v_exp_f32_e32 v73, v73
	v_exp_f32_e32 v74, v74
	v_exp_f32_e32 v75, v75
	s_waitcnt lgkmcnt(10)
	v_mfma_f32_32x32x16_bf16 v[4:19], v[148:151], v[88:91], v[4:19]
	v_exp_f32_e32 v76, v76
	v_exp_f32_e32 v77, v77
	v_exp_f32_e32 v78, v78
	v_exp_f32_e32 v79, v79
	s_waitcnt lgkmcnt(8)
	v_mfma_f32_32x32x16_bf16 v[20:35], v[148:151], v[92:95], v[20:35]
	v_exp_f32_e32 v80, v80
	v_exp_f32_e32 v81, v81
	v_exp_f32_e32 v82, v82
	v_exp_f32_e32 v83, v83
	s_waitcnt lgkmcnt(6)
	v_mfma_f32_32x32x16_bf16 v[4:19], v[140:143], v[96:99], v[4:19]
	v_exp_f32_e32 v36, v36
	v_exp_f32_e32 v37, v37
	v_exp_f32_e32 v38, v38
	v_exp_f32_e32 v39, v39
	s_waitcnt lgkmcnt(4)
	v_mfma_f32_32x32x16_bf16 v[20:35], v[140:143], v[52:55], v[20:35]
	v_exp_f32_e32 v40, v40
	v_exp_f32_e32 v41, v41
	v_exp_f32_e32 v42, v42
	v_exp_f32_e32 v43, v43
	s_waitcnt lgkmcnt(2)
	v_mfma_f32_32x32x16_bf16 v[4:19], v[132:135], v[56:59], v[4:19]
	v_exp_f32_e32 v44, v44
	v_exp_f32_e32 v45, v45
	v_exp_f32_e32 v46, v46
	v_exp_f32_e32 v47, v47
	s_waitcnt lgkmcnt(0)
	v_mfma_f32_32x32x16_bf16 v[20:35], v[132:135], v[60:63], v[20:35]
	v_exp_f32_e32 v48, v48
	v_exp_f32_e32 v49, v49
	v_exp_f32_e32 v50, v50
	v_exp_f32_e32 v51, v51
	v_add_f32_e32 v52, v68, v69
	v_add_f32_e32 v52, v70, v52
	v_add_f32_e32 v52, v71, v52
	v_add_f32_e32 v52, v72, v52
	v_add_f32_e32 v52, v73, v52
	v_add_f32_e32 v52, v74, v52
	v_add_f32_e32 v52, v75, v52
	v_add_f32_e32 v52, v76, v52
	v_add_f32_e32 v52, v77, v52
	v_add_f32_e32 v52, v78, v52
	v_add_f32_e32 v52, v79, v52
	v_add_f32_e32 v52, v80, v52
	v_add_f32_e32 v52, v81, v52
	v_add_f32_e32 v52, v82, v52
	v_add_f32_e32 v52, v83, v52
	v_add_f32_e32 v52, v36, v52
	v_add_f32_e32 v52, v37, v52
	v_add_f32_e32 v52, v38, v52
	v_add_f32_e32 v52, v39, v52
	v_add_f32_e32 v52, v40, v52
	v_add_f32_e32 v52, v41, v52
	v_add_f32_e32 v52, v42, v52
	v_add_f32_e32 v52, v43, v52
	v_add_f32_e32 v52, v44, v52
	v_add_f32_e32 v52, v45, v52
	v_add_f32_e32 v52, v46, v52
	v_add_f32_e32 v52, v47, v52
	v_add_f32_e32 v52, v48, v52
	v_add_f32_e32 v52, v49, v52
	v_add_f32_e32 v52, v50, v52
	v_add_f32_e32 v52, v51, v52
	v_add_f32_e32 v1, v1, v100
	v_add_f32_e32 v1, v1, v52
	v_cvt_pk_bf16_f32 v52, v68, v69
	v_cvt_pk_bf16_f32 v53, v70, v71
	v_cvt_pk_bf16_f32 v54, v72, v73
	v_cvt_pk_bf16_f32 v55, v74, v75
	v_cvt_pk_bf16_f32 v56, v76, v77
	v_cvt_pk_bf16_f32 v57, v78, v79
	v_cvt_pk_bf16_f32 v58, v80, v81
	v_cvt_pk_bf16_f32 v59, v82, v83
	v_cvt_pk_bf16_f32 v36, v36, v37
	v_cvt_pk_bf16_f32 v37, v38, v39
	v_cvt_pk_bf16_f32 v38, v40, v41
	v_cvt_pk_bf16_f32 v39, v42, v43
	v_cvt_pk_bf16_f32 v40, v44, v45
	v_cvt_pk_bf16_f32 v41, v46, v47
	v_cvt_pk_bf16_f32 v42, v48, v49
	v_cvt_pk_bf16_f32 v43, v50, v51
	v_add3_u32 v0, v0, v3, s24
	ds_read_b64_tr_b16 v[44:45],v0 offset:0
	ds_read_b64_tr_b16 v[46:47],v0 offset:512
	ds_read_b64_tr_b16 v[48:49],v0 offset:1024
	ds_read_b64_tr_b16 v[50:51],v0 offset:1536
	ds_read_b64_tr_b16 v[60:61],v0 offset:2048
	ds_read_b64_tr_b16 v[62:63],v0 offset:2560
	ds_read_b64_tr_b16 v[64:65],v0 offset:3072
	ds_read_b64_tr_b16 v[66:67],v0 offset:3584
	s_waitcnt lgkmcnt(0)
	s_nop 0
	v_mfma_f32_32x32x16_bf16 v[4:19], v[52:55], v[44:47], v[4:19]
	ds_read_b64_tr_b16 v[44:45],v0 offset:4096
	ds_read_b64_tr_b16 v[46:47],v0 offset:4608
	v_mfma_f32_32x32x16_bf16 v[4:19], v[56:59], v[48:51], v[4:19]
	ds_read_b64_tr_b16 v[48:49],v0 offset:5120
	ds_read_b64_tr_b16 v[50:51],v0 offset:5632
	v_mfma_f32_32x32x16_bf16 v[4:19], v[36:39], v[60:63], v[4:19]
	ds_read_b64_tr_b16 v[60:61],v0 offset:6144
	ds_read_b64_tr_b16 v[62:63],v0 offset:6656
	v_mfma_f32_32x32x16_bf16 v[4:19], v[40:43], v[64:67], v[4:19]
	ds_read_b64_tr_b16 v[64:65],v0 offset:7168
	ds_read_b64_tr_b16 v[66:67],v0 offset:7680
	s_waitcnt lgkmcnt(0)
	v_mfma_f32_32x32x16_bf16 v[20:35], v[52:55], v[44:47], v[20:35]
	v_mfma_f32_32x32x16_bf16 v[20:35], v[56:59], v[48:51], v[20:35]
	v_mfma_f32_32x32x16_bf16 v[20:35], v[36:39], v[60:63], v[20:35]
	v_mfma_f32_32x32x16_bf16 v[20:35], v[40:43], v[64:67], v[20:35]
	s_setprio 0
	v_mov_b32_e32 v0, v1
	s_nop 1
	v_permlane32_swap_b32_e32 v1, v0
	v_cmp_gt_u32_e32 vcc, 32, v186
	s_and_saveexec_b64 s[24:25], vcc
	s_cbranch_execz .LBB0_727
	v_lshl_add_u32 v3, v188, 2, s28
	v_add_f32_e32 v0, v1, v0
	ds_write_b32 v3, v0 offset:49280
	s_branch .LBB0_727
